# grid barrier without a release hop: every workgroup polls the cross-XCC arrival counter against (round+1)*XCCs; no generation words, XCC leaders still write back L2 before arriving
# baseline (speedup 1.0000x reference)
; __device__ __forceinline__ unsigned xb_ld(unsigned* p)              { return __hip_atomic_load(p, __ATOMIC_RELAXED, __HIP_MEMORY_SCOPE_AGENT); }
; __device__ __forceinline__ unsigned xb_add(unsigned* p, unsigned v) { return __hip_atomic_fetch_add(p, v, __ATOMIC_RELAXED, __HIP_MEMORY_SCOPE_AGENT); }
; #define XB_SPIN(cond, bar) do { unsigned _sp = 0; while (cond) { __builtin_amdgcn_s_sleep(1); \
;     if ((++_sp & 255u) == 0u) { if (xb_ld(&(bar)[XB_TMO])) break; if (_sp > XB_SPIN_CAP) { atomicAdd(&(bar)[XB_TMO], 1u); break; } } } } while (0)
; __device__ __forceinline__ void xcd_barrier(const XcdBarrier& b, const int tid) {
;     ...
;         const unsigned old = xb_add(&bar[XB_XSUB(b.x)], 1u);
;         const unsigned gen = old / nloc;
;         if (old + 1u == (gen + 1u) * nloc) {
;             __builtin_amdgcn_fence(__ATOMIC_RELEASE, "agent");
;             asm volatile("s_waitcnt vmcnt(0)" ::: "memory");
;             const unsigned og = xb_add(&bar[XB_TOP], 1u);
;             const unsigned tg = og / nx;
;             if (og + 1u == (tg + 1u) * nx) xb_add(&bar[XB_TOPGEN], 1u);
;             else XB_SPIN(xb_ld(&bar[XB_TOPGEN]) == tg, bar);
;             __builtin_amdgcn_fence(__ATOMIC_ACQUIRE, "agent");
;             xb_add(&bar[XB_XGEN(b.x)], 1u);
;             asm volatile("s_waitcnt vmcnt(0)" ::: "memory");
;         } else {
;             XB_SPIN(xb_ld(&bar[XB_XGEN(b.x)]) == gen, bar);
.LBB0_588:
	s_or_b64 exec, exec, s[2:3]
	v_cvt_f32_u32_e32 v5, v3
	s_waitcnt vmcnt(0)
	v_readfirstlane_b32 s2, v4
	v_sub_u32_e32 v4, 0, v3
	v_rcp_iflag_f32_e32 v5, v5
	v_add_u32_e32 v6, s2, v0
	v_mul_f32_e32 v5, 0x4f7ffffe, v5
	v_cvt_u32_f32_e32 v5, v5
	v_mul_lo_u32 v0, v4, v5
	v_mul_hi_u32 v0, v5, v0
	v_add_u32_e32 v0, v5, v0
	v_mul_hi_u32 v0, v6, v0
	v_mul_lo_u32 v4, v0, v3
	v_sub_u32_e32 v4, v6, v4
	v_add_u32_e32 v5, 1, v0
	v_cmp_ge_u32_e32 vcc, v4, v3
	s_nop 1
	v_cndmask_b32_e32 v0, v0, v5, vcc
	v_sub_u32_e32 v5, v4, v3
	v_cndmask_b32_e32 v4, v4, v5, vcc
	v_add_u32_e32 v5, 1, v0
	v_cmp_ge_u32_e32 vcc, v4, v3
	v_add_u32_e32 v4, 1, v6
	s_nop 0
	v_cndmask_b32_e32 v0, v0, v5, vcc
	v_mul_lo_u32 v5, v3, v0
	v_add_u32_e32 v3, v5, v3
	v_cmp_ne_u32_e32 vcc, v4, v3
	s_and_saveexec_b64 s[2:3], vcc
	s_xor_b64 s[2:3], exec, s[2:3]
	s_cbranch_execz .LBB0_602
	v_readlane_b32 s4, v250, 13
	v_readlane_b32 s5, v250, 14
	s_waitcnt lgkmcnt(0)
	v_add_u32_e32 v0, 1, v0
	v_mul_lo_u32 v0, v0, v2
	s_nop 3
	global_load_dword v2, v1, s[4:5] sc1
	s_waitcnt vmcnt(0)
	v_cmp_lt_u32_e32 vcc, v2, v0
	s_and_saveexec_b64 s[4:5], vcc
	s_cbranch_execz .LBB0_601
	s_mov_b32 s20, 1
	s_mov_b64 s[6:7], 0
	s_branch .LBB0_592

; __device__ __forceinline__ unsigned xb_ld(unsigned* p)              { return __hip_atomic_load(p, __ATOMIC_RELAXED, __HIP_MEMORY_SCOPE_AGENT); }
; #define XB_SPIN(cond, bar) do { unsigned _sp = 0; while (cond) { __builtin_amdgcn_s_sleep(1); \
;     if ((++_sp & 255u) == 0u) { if (xb_ld(&(bar)[XB_TMO])) break; if (_sp > XB_SPIN_CAP) { atomicAdd(&(bar)[XB_TMO], 1u); break; } } } } while (0)
; __device__ __forceinline__ void xcd_barrier(const XcdBarrier& b, const int tid) {
;     ...
;             XB_SPIN(xb_ld(&bar[XB_XGEN(b.x)]) == gen, bar);
.LBB0_596:
	v_readlane_b32 s10, v250, 13
	v_readlane_b32 s11, v250, 14
	s_add_i32 s20, s20, 1
	s_mov_b64 s[30:31], -1
	s_nop 2
	global_load_dword v2, v1, s[10:11] sc1
	s_waitcnt vmcnt(0)
	v_cmp_ge_u32_e32 vcc, v2, v0
	s_orn2_b64 s[10:11], vcc, exec
	s_branch .LBB0_591

; __device__ __forceinline__ unsigned xb_ld(unsigned* p)              { return __hip_atomic_load(p, __ATOMIC_RELAXED, __HIP_MEMORY_SCOPE_AGENT); }
; __device__ __forceinline__ unsigned xb_add(unsigned* p, unsigned v) { return __hip_atomic_fetch_add(p, v, __ATOMIC_RELAXED, __HIP_MEMORY_SCOPE_AGENT); }
; #define XB_SPIN(cond, bar) do { unsigned _sp = 0; while (cond) { __builtin_amdgcn_s_sleep(1); \
;     if ((++_sp & 255u) == 0u) { if (xb_ld(&(bar)[XB_TMO])) break; if (_sp > XB_SPIN_CAP) { atomicAdd(&(bar)[XB_TMO], 1u); break; } } } } while (0)
; __device__ __forceinline__ void xcd_barrier(const XcdBarrier& b, const int tid) {
;     ...
;             const unsigned og = xb_add(&bar[XB_TOP], 1u);
;             const unsigned tg = og / nx;
;             if (og + 1u == (tg + 1u) * nx) xb_add(&bar[XB_TOPGEN], 1u);
;             else XB_SPIN(xb_ld(&bar[XB_TOPGEN]) == tg, bar);
;             __builtin_amdgcn_fence(__ATOMIC_ACQUIRE, "agent");
;             xb_add(&bar[XB_XGEN(b.x)], 1u);
;             asm volatile("s_waitcnt vmcnt(0)" ::: "memory");
;         } else {
;             XB_SPIN(xb_ld(&bar[XB_XGEN(b.x)]) == gen, bar);
.LBB0_605:
	s_or_b64 exec, exec, s[4:5]
	s_waitcnt vmcnt(0)
	v_readfirstlane_b32 s2, v3
	v_sub_u32_e32 v4, 0, v2
	s_mov_b64 s[4:5], 0
	v_add_u32_e32 v3, s2, v0
	v_cvt_f32_u32_e32 v0, v2
	v_readlane_b32 s2, v250, 15
	v_readlane_b32 s3, v250, 16
	v_rcp_iflag_f32_e32 v0, v0
	s_nop 0
	v_mul_f32_e32 v0, 0x4f7ffffe, v0
	v_cvt_u32_f32_e32 v0, v0
	v_mul_lo_u32 v4, v4, v0
	v_mul_hi_u32 v4, v0, v4
	v_add_u32_e32 v0, v0, v4
	v_mul_hi_u32 v0, v3, v0
	v_mul_lo_u32 v4, v0, v2
	v_sub_u32_e32 v4, v3, v4
	v_cmp_ge_u32_e32 vcc, v4, v2
	v_add_u32_e32 v5, 1, v0
	v_add_u32_e32 v3, 1, v3
	v_cndmask_b32_e32 v0, v0, v5, vcc
	v_sub_u32_e32 v5, v4, v2
	v_cndmask_b32_e32 v4, v4, v5, vcc
	v_cmp_ge_u32_e32 vcc, v4, v2
	v_add_u32_e32 v4, 1, v0
	s_nop 0
	v_cndmask_b32_e32 v0, v0, v4, vcc
	v_mul_lo_u32 v4, v2, v0
	v_add_u32_e32 v2, v4, v2
	v_cmp_ne_u32_e32 vcc, v3, v2
	v_mov_b32_e32 v0, v2
	v_mov_b64_e32 v[2:3], s[2:3]
	s_and_saveexec_b64 s[2:3], vcc
	s_cbranch_execz .LBB0_617
	v_readlane_b32 s4, v250, 13
	v_readlane_b32 s5, v250, 14
	s_mov_b64 s[6:7], 0
	s_nop 3
	global_load_dword v2, v1, s[4:5] sc1
	s_waitcnt vmcnt(0)
	v_cmp_lt_u32_e32 vcc, v2, v0
	s_and_saveexec_b64 s[4:5], vcc
	s_cbranch_execz .LBB0_616
	s_mov_b32 s20, 1
	s_branch .LBB0_609
